# P3 as 256 balanced 160-row units; helper weight conversions split over idle tails of P2/P5/P9; P7,P10 160-row; P0 loads batched
# speedup vs baseline: 1.0034x; 1.0034x over previous
.LBB0_181:
	v_add_u32_e32 v18, s1, v16
	v_add_u32_e32 v20, 2, v18
	v_add_u32_e32 v22, 4, v18
	v_add_u32_e32 v24, 6, v18
	v_ashrrev_i32_e32 v19, 31, v18
	v_add_u32_e32 v26, 8, v18
	v_add_u32_e32 v28, 10, v18
	v_add_u32_e32 v30, 12, v18
	v_add_u32_e32 v32, 14, v18
	v_ashrrev_i32_e32 v21, 31, v20
	v_ashrrev_i32_e32 v23, 31, v22
	v_ashrrev_i32_e32 v25, 31, v24
	v_lshlrev_b64 v[18:19], 12, v[18:19]
	v_ashrrev_i32_e32 v27, 31, v26
	v_ashrrev_i32_e32 v29, 31, v28
	v_ashrrev_i32_e32 v31, 31, v30
	v_ashrrev_i32_e32 v33, 31, v32
	v_lshlrev_b64 v[20:21], 12, v[20:21]
	v_lshlrev_b64 v[22:23], 12, v[22:23]
	v_lshlrev_b64 v[24:25], 12, v[24:25]
	v_lshl_add_u64 v[18:19], v[6:7], 0, v[18:19]
	v_lshlrev_b64 v[26:27], 12, v[26:27]
	v_lshlrev_b64 v[28:29], 12, v[28:29]
	v_lshlrev_b64 v[30:31], 12, v[30:31]
	v_lshlrev_b64 v[32:33], 12, v[32:33]
	v_lshl_add_u64 v[20:21], v[6:7], 0, v[20:21]
	v_lshl_add_u64 v[22:23], v[6:7], 0, v[22:23]
	v_lshl_add_u64 v[24:25], v[6:7], 0, v[24:25]
	v_lshl_add_u64 v[26:27], v[6:7], 0, v[26:27]
	v_lshl_add_u64 v[28:29], v[6:7], 0, v[28:29]
	v_lshl_add_u64 v[30:31], v[6:7], 0, v[30:31]
	v_lshl_add_u64 v[32:33], v[6:7], 0, v[32:33]
	global_load_dword v100, v[18:19], off nt
	s_nop 0
	global_load_dword v101, v[20:21], off nt
	s_nop 0
	global_load_dword v102, v[22:23], off nt
	global_load_dword v103, v[24:25], off nt
	s_nop 0
	global_load_dword v104, v[26:27], off nt
	global_load_dword v105, v[28:29], off nt
	global_load_dword v106, v[30:31], off nt
	global_load_dword v107, v[32:33], off nt
	s_add_i32 s1, s1, 16
	v_add_u32_e32 v18, s1, v16
	v_add_u32_e32 v20, 2, v18
	v_add_u32_e32 v22, 4, v18
	v_add_u32_e32 v24, 6, v18
	v_ashrrev_i32_e32 v19, 31, v18
	v_add_u32_e32 v26, 8, v18
	v_add_u32_e32 v28, 10, v18
	v_add_u32_e32 v30, 12, v18
	v_add_u32_e32 v32, 14, v18
	v_ashrrev_i32_e32 v21, 31, v20
	v_ashrrev_i32_e32 v23, 31, v22
	v_ashrrev_i32_e32 v25, 31, v24
	v_lshlrev_b64 v[18:19], 12, v[18:19]
	v_ashrrev_i32_e32 v27, 31, v26
	v_ashrrev_i32_e32 v29, 31, v28
	v_ashrrev_i32_e32 v31, 31, v30
	v_ashrrev_i32_e32 v33, 31, v32
	v_lshlrev_b64 v[20:21], 12, v[20:21]
	v_lshlrev_b64 v[22:23], 12, v[22:23]
	v_lshlrev_b64 v[24:25], 12, v[24:25]
	v_lshl_add_u64 v[18:19], v[6:7], 0, v[18:19]
	v_lshlrev_b64 v[26:27], 12, v[26:27]
	v_lshlrev_b64 v[28:29], 12, v[28:29]
	v_lshlrev_b64 v[30:31], 12, v[30:31]
	v_lshlrev_b64 v[32:33], 12, v[32:33]
	v_lshl_add_u64 v[20:21], v[6:7], 0, v[20:21]
	v_lshl_add_u64 v[22:23], v[6:7], 0, v[22:23]
	v_lshl_add_u64 v[24:25], v[6:7], 0, v[24:25]
	v_lshl_add_u64 v[26:27], v[6:7], 0, v[26:27]
	v_lshl_add_u64 v[28:29], v[6:7], 0, v[28:29]
	v_lshl_add_u64 v[30:31], v[6:7], 0, v[30:31]
	v_lshl_add_u64 v[32:33], v[6:7], 0, v[32:33]
	global_load_dword v108, v[18:19], off nt
	s_nop 0
	global_load_dword v109, v[20:21], off nt
	s_nop 0
	global_load_dword v110, v[22:23], off nt
	global_load_dword v111, v[24:25], off nt
	s_nop 0
	global_load_dword v112, v[26:27], off nt
	global_load_dword v113, v[28:29], off nt
	global_load_dword v114, v[30:31], off nt
	global_load_dword v115, v[32:33], off nt
	s_add_i32 s1, s1, 16
	v_add_u32_e32 v18, s1, v16
	v_add_u32_e32 v20, 2, v18
	v_add_u32_e32 v22, 4, v18
	v_add_u32_e32 v24, 6, v18
	v_ashrrev_i32_e32 v19, 31, v18
	v_add_u32_e32 v26, 8, v18
	v_add_u32_e32 v28, 10, v18
	v_add_u32_e32 v30, 12, v18
	v_add_u32_e32 v32, 14, v18
	v_ashrrev_i32_e32 v21, 31, v20
	v_ashrrev_i32_e32 v23, 31, v22
	v_ashrrev_i32_e32 v25, 31, v24
	v_lshlrev_b64 v[18:19], 12, v[18:19]
	v_ashrrev_i32_e32 v27, 31, v26
	v_ashrrev_i32_e32 v29, 31, v28
	v_ashrrev_i32_e32 v31, 31, v30
	v_ashrrev_i32_e32 v33, 31, v32
	v_lshlrev_b64 v[20:21], 12, v[20:21]
	v_lshlrev_b64 v[22:23], 12, v[22:23]
	v_lshlrev_b64 v[24:25], 12, v[24:25]
	v_lshl_add_u64 v[18:19], v[6:7], 0, v[18:19]
	v_lshlrev_b64 v[26:27], 12, v[26:27]
	v_lshlrev_b64 v[28:29], 12, v[28:29]
	v_lshlrev_b64 v[30:31], 12, v[30:31]
	v_lshlrev_b64 v[32:33], 12, v[32:33]
	v_lshl_add_u64 v[20:21], v[6:7], 0, v[20:21]
	v_lshl_add_u64 v[22:23], v[6:7], 0, v[22:23]
	v_lshl_add_u64 v[24:25], v[6:7], 0, v[24:25]
	v_lshl_add_u64 v[26:27], v[6:7], 0, v[26:27]
	v_lshl_add_u64 v[28:29], v[6:7], 0, v[28:29]
	v_lshl_add_u64 v[30:31], v[6:7], 0, v[30:31]
	v_lshl_add_u64 v[32:33], v[6:7], 0, v[32:33]
	global_load_dword v116, v[18:19], off nt
	s_nop 0
	global_load_dword v117, v[20:21], off nt
	s_nop 0
	global_load_dword v118, v[22:23], off nt
	global_load_dword v119, v[24:25], off nt
	s_nop 0
	global_load_dword v120, v[26:27], off nt
	global_load_dword v121, v[28:29], off nt
	global_load_dword v122, v[30:31], off nt
	global_load_dword v123, v[32:33], off nt
	s_add_i32 s1, s1, 16
	v_add_u32_e32 v18, s1, v16
	v_add_u32_e32 v20, 2, v18
	v_add_u32_e32 v22, 4, v18
	v_add_u32_e32 v24, 6, v18
	v_ashrrev_i32_e32 v19, 31, v18
	v_add_u32_e32 v26, 8, v18
	v_add_u32_e32 v28, 10, v18
	v_add_u32_e32 v30, 12, v18
	v_add_u32_e32 v32, 14, v18
	v_ashrrev_i32_e32 v21, 31, v20
	v_ashrrev_i32_e32 v23, 31, v22
	v_ashrrev_i32_e32 v25, 31, v24
	v_lshlrev_b64 v[18:19], 12, v[18:19]
	v_ashrrev_i32_e32 v27, 31, v26
	v_ashrrev_i32_e32 v29, 31, v28
	v_ashrrev_i32_e32 v31, 31, v30
	v_ashrrev_i32_e32 v33, 31, v32
	v_lshlrev_b64 v[20:21], 12, v[20:21]
	v_lshlrev_b64 v[22:23], 12, v[22:23]
	v_lshlrev_b64 v[24:25], 12, v[24:25]
	v_lshl_add_u64 v[18:19], v[6:7], 0, v[18:19]
	v_lshlrev_b64 v[26:27], 12, v[26:27]
	v_lshlrev_b64 v[28:29], 12, v[28:29]
	v_lshlrev_b64 v[30:31], 12, v[30:31]
	v_lshlrev_b64 v[32:33], 12, v[32:33]
	v_lshl_add_u64 v[20:21], v[6:7], 0, v[20:21]
	v_lshl_add_u64 v[22:23], v[6:7], 0, v[22:23]
	v_lshl_add_u64 v[24:25], v[6:7], 0, v[24:25]
	v_lshl_add_u64 v[26:27], v[6:7], 0, v[26:27]
	v_lshl_add_u64 v[28:29], v[6:7], 0, v[28:29]
	v_lshl_add_u64 v[30:31], v[6:7], 0, v[30:31]
	v_lshl_add_u64 v[32:33], v[6:7], 0, v[32:33]
	global_load_dword v124, v[18:19], off nt
	s_nop 0
	global_load_dword v125, v[20:21], off nt
	s_nop 0
	global_load_dword v126, v[22:23], off nt
	global_load_dword v127, v[24:25], off nt
	s_nop 0
	global_load_dword v128, v[26:27], off nt
	global_load_dword v129, v[28:29], off nt
	global_load_dword v130, v[30:31], off nt
	global_load_dword v131, v[32:33], off nt
	v_add_u32_e32 v132, 0x400, v17
	v_add_u32_e32 v133, 0x840, v17
	v_add_u32_e32 v134, 0xc40, v17
	v_add_u32_e32 v135, 0x1080, v17
	v_add_u32_e32 v136, 0x1480, v17
	v_add_u32_e32 v137, 0x18c0, v17
	v_add_u32_e32 v138, 0x1cc0, v17
	s_waitcnt vmcnt(30)
	ds_write2_b32 v17, v100, v101 offset1:66
	s_waitcnt vmcnt(28)
	ds_write2_b32 v17, v102, v103 offset0:132 offset1:198
	s_waitcnt vmcnt(26)
	ds_write2_b32 v132, v104, v105 offset0:8 offset1:74
	s_waitcnt vmcnt(24)
	ds_write2_b32 v132, v106, v107 offset0:140 offset1:206
	s_waitcnt vmcnt(22)
	ds_write2_b32 v133, v108, v109 offset1:66
	s_waitcnt vmcnt(20)
	ds_write2_b32 v133, v110, v111 offset0:132 offset1:198
	s_waitcnt vmcnt(18)
	ds_write2_b32 v134, v112, v113 offset0:8 offset1:74
	s_waitcnt vmcnt(16)
	ds_write2_b32 v134, v114, v115 offset0:140 offset1:206
	s_waitcnt vmcnt(14)
	ds_write2_b32 v135, v116, v117 offset1:66
	s_waitcnt vmcnt(12)
	ds_write2_b32 v135, v118, v119 offset0:132 offset1:198
	s_waitcnt vmcnt(10)
	ds_write2_b32 v136, v120, v121 offset0:8 offset1:74
	s_waitcnt vmcnt(8)
	ds_write2_b32 v136, v122, v123 offset0:140 offset1:206
	s_waitcnt vmcnt(6)
	ds_write2_b32 v137, v124, v125 offset1:66
	s_waitcnt vmcnt(4)
	ds_write2_b32 v137, v126, v127 offset0:132 offset1:198
	s_waitcnt vmcnt(2)
	ds_write2_b32 v138, v128, v129 offset0:8 offset1:74
	s_waitcnt vmcnt(0)
	ds_write2_b32 v138, v130, v131 offset0:140 offset1:206
	s_waitcnt lgkmcnt(0)
	ds_read2_b32 v[6:7], v9 offset0:33 offset1:41
	ds_read2_b32 v[20:21], v9 offset1:8
	ds_read2_b32 v[22:23], v9 offset0:66 offset1:74
	ds_read2_b32 v[24:25], v9 offset0:99 offset1:107
	ds_read2_b32 v[26:27], v9 offset0:132 offset1:140
	ds_read2_b32 v[28:29], v9 offset0:165 offset1:173
	ds_read2_b32 v[30:31], v9 offset0:198 offset1:206
	ds_read2_b32 v[32:33], v9 offset0:231 offset1:239
	s_waitcnt lgkmcnt(6)
	v_cvt_pk_bf16_f32 v16, v20, v6
	v_or_b32_e32 v6, s0, v8
	v_lshlrev_b32_e32 v6, 2, v6
	v_bitop3_b32 v20, s0, v14, v8 bitop3:0xc8
	v_and_or_b32 v6, v6, 16, v20
	s_ashr_i32 s7, s6, 31
	v_mul_u32_u24_e32 v36, 0x1600, v6
	v_lshl_add_u64 v[34:35], s[6:7], 1, v[4:5]
	v_ashrrev_i32_e32 v37, 31, v36
	v_or_b32_e32 v6, s0, v10
	s_waitcnt lgkmcnt(4)
	v_cvt_pk_bf16_f32 v17, v22, v24
	s_waitcnt lgkmcnt(2)
	v_cvt_pk_bf16_f32 v18, v26, v28
	s_waitcnt lgkmcnt(0)
	v_cvt_pk_bf16_f32 v19, v30, v32
	v_lshl_add_u64 v[36:37], v[34:35], 0, v[36:37]
	v_lshlrev_b32_e32 v6, 2, v6
	global_store_dwordx4 v[36:37], v[16:19], off
	v_and_b32_e32 v6, 16, v6
	s_add_i32 s8, s8, s9
	v_cvt_pk_bf16_f32 v16, v21, v7
	v_bitop3_b32 v7, s0, v15, v10 bitop3:0xc8
	v_or3_b32 v6, v7, v6, 4
	v_cvt_pk_bf16_f32 v17, v23, v25
	v_cvt_pk_bf16_f32 v18, v27, v29
	v_cvt_pk_bf16_f32 v19, v31, v33
	v_mad_i64_i32 v[6:7], s[6:7], v6, s10, v[34:35]
	ds_read2_b32 v[20:21], v9 offset0:16 offset1:24
	ds_read2_b32 v[22:23], v9 offset0:49 offset1:57
	ds_read2_b32 v[24:25], v9 offset0:82 offset1:90
	ds_read2_b32 v[26:27], v9 offset0:115 offset1:123
	ds_read2_b32 v[28:29], v9 offset0:148 offset1:156
	ds_read2_b32 v[30:31], v9 offset0:181 offset1:189
	ds_read2_b32 v[32:33], v9 offset0:214 offset1:222
	ds_read2_b32 v[36:37], v9 offset0:247 offset1:255
	global_store_dwordx4 v[6:7], v[16:19], off
	v_or_b32_e32 v6, s0, v11
	v_lshlrev_b32_e32 v6, 2, v6
	v_and_b32_e32 v6, 16, v6
	v_bitop3_b32 v7, s0, v15, v11 bitop3:0xc8
	v_or3_b32 v6, v7, v6, 8
	s_waitcnt lgkmcnt(6)
	v_cvt_pk_bf16_f32 v16, v20, v22
	s_waitcnt lgkmcnt(4)
	v_cvt_pk_bf16_f32 v17, v24, v26
	s_waitcnt lgkmcnt(2)
	v_cvt_pk_bf16_f32 v18, v28, v30
	s_waitcnt lgkmcnt(0)
	v_cvt_pk_bf16_f32 v19, v32, v36
	v_mad_i64_i32 v[6:7], s[6:7], v6, s10, v[34:35]
	global_store_dwordx4 v[6:7], v[16:19], off
	v_or_b32_e32 v6, s0, v12
	v_lshlrev_b32_e32 v6, 2, v6
	v_and_b32_e32 v6, 16, v6
	v_bitop3_b32 v7, s0, v15, v12 bitop3:0xc8
	v_or3_b32 v6, v7, v6, 12
	v_cvt_pk_bf16_f32 v16, v21, v23
	v_cvt_pk_bf16_f32 v17, v25, v27
	v_cvt_pk_bf16_f32 v18, v29, v31
	v_cvt_pk_bf16_f32 v19, v33, v37
	v_mad_i64_i32 v[6:7], s[0:1], v6, s10, v[34:35]
	global_store_dwordx4 v[6:7], v[16:19], off
	s_waitcnt lgkmcnt(0)
	s_cmpk_lt_i32 s8, 0x580
	s_cbranch_scc1 .LBB0_180
.Ld1a_begin:
	s_mov_b64 s[98:99], s[4:5]
	s_sub_u32 s100, s94, 0xb8
	s_subb_u32 s101, s95, 0
	s_load_dwordx4 s[44:47], s[100:101], 0x60
	s_load_dwordx2 s[48:49], s[100:101], 0x70
	s_load_dwordx2 s[58:59], s[100:101], 0x18
	s_load_dwordx2 s[60:61], s[100:101], 0x20
	s_waitcnt lgkmcnt(0)
	s_cmpk_gt_i32 s3, 0x70
	s_cselect_b32 s12, 0x70, 0
	s_cmp_lt_i32 s2, s12
	s_cbranch_scc1 .Ld1a_end
	s_sub_i32 s0, s2, s12
	s_lshl_b32 s13, s0, 3
	s_add_i32 s13, s13, s33
	s_sub_i32 s14, s3, s12
	s_cmpk_gt_u32 s13, 0x197f
	s_cbranch_scc1 .Ld1a_318
	v_lshlrev_b32_e32 v2, 3, v0
	s_lshl_b32 s4, s33, 14
	v_lshrrev_b32_e32 v19, 3, v164
	v_and_b32_e32 v26, 56, v2
	s_add_i32 s0, s4, 0
	v_mul_u32_u24_e32 v2, 0x84, v26
	v_lshlrev_b32_e32 v13, 2, v19
	v_mov_b32_e32 v3, 0
	v_add3_u32 v44, s0, v2, v13
	v_lshlrev_b32_e32 v2, 1, v26
	v_lshl_add_u64 v[10:11], s[28:29], 0, v[2:3]
	s_mov_b64 s[0:1], 0x2900000
	v_lshl_add_u64 v[4:5], v[10:11], 0, s[0:1]
	s_mov_b64 s[0:1], 0x2300000
	s_lshl_b32 s15, s14, 3
	v_lshl_add_u64 v[6:7], v[10:11], 0, s[0:1]
	s_mov_b64 s[0:1], 0x1d80000
	s_add_u32 s18, s28, 0x2e00000
	v_lshl_add_u64 v[8:9], v[10:11], 0, s[0:1]
	s_mov_b64 s[0:1], 0x1280000
	s_addc_u32 s19, s29, 0
	v_lshl_add_u64 v[10:11], v[10:11], 0, s[0:1]
	s_lshl_b32 s0, s2, 3
	v_lshrrev_b32_e32 v1, 5, v164
	v_mov_b32_e32 v2, 0x6000
	s_add_i32 s0, s33, s0
	s_lshl_b32 s1, s12, 3
	v_and_b32_e32 v12, 31, v0
	v_lshl_or_b32 v49, v19, 13, v2
	v_mul_u32_u24_e32 v2, 0x84, v1
	s_sub_i32 s0, s0, s1
	v_and_b32_e32 v48, 16, v13
	v_or_b32_e32 v55, 0x80c, v13
	v_or_b32_e32 v56, 12, v13
	v_or_b32_e32 v13, s4, v2
	v_lshlrev_b32_e32 v2, 2, v12
	s_add_i32 s20, s0, 0xffffe780
	s_lshl_b32 s0, s3, 8
	s_lshl_b32 s1, s12, 8
	v_bfe_u32 v18, v0, 5, 1
	v_add3_u32 v57, v13, v2, 0
	v_lshl_add_u64 v[12:13], s[60:61], 0, v[2:3]
	s_sub_i32 s22, s0, s1
	s_lshl_b32 s0, s3, 5
	s_lshl_b32 s1, s12, 5
	v_readlane_b32 s60, v244, 0
	v_mul_u32_u24_e32 v20, 0x3000, v18
	s_sub_i32 s24, s0, s1
	v_readlane_b32 s61, v244, 1
	v_readlane_b32 s64, v244, 4
	v_readlane_b32 s65, v244, 5
	s_lshl_b32 s0, s13, 1
	s_lshl_b32 s1, s3, 4
	s_lshl_b32 s4, s12, 4
	v_mul_hi_u32_u24_e32 v21, 0x3000, v18
	v_or_b32_e32 v20, v20, v2
	s_mov_b32 s5, 0
	v_or_b32_e32 v45, 8, v19
	v_or_b32_e32 v46, 16, v19
	v_or_b32_e32 v47, 24, v19
	v_or_b32_e32 v50, 0x800, v48
	v_or_b32_e32 v51, 0x804, v48
	v_or_b32_e32 v52, 4, v48
	v_or_b32_e32 v53, 0x808, v48
	v_or_b32_e32 v54, 8, v48
	s_lshl_b32 s21, s13, 5
	v_or_b32_e32 v58, 14, v1
	s_lshl_b32 s23, s13, 2
	v_or_b32_e32 v59, 12, v1
	v_or_b32_e32 v60, 10, v1
	v_or_b32_e32 v61, 8, v1
	v_or_b32_e32 v62, 6, v1
	v_or_b32_e32 v63, 4, v1
	v_or_b32_e32 v64, 2, v1
	v_lshl_add_u64 v[14:15], s[64:65], 0, v[2:3]
	s_add_i32 s25, s0, 0x7fffd300
	s_sub_i32 s26, s1, s4
	v_lshl_add_u64 v[16:17], s[48:49], 0, v[2:3]
	v_lshl_add_u64 v[20:21], s[48:49], 0, v[20:21]
	v_lshl_add_u64 v[22:23], s[46:47], 0, v[2:3]
	s_add_i32 s27, s0, 0x7fffea00
	v_lshl_add_u64 v[24:25], s[44:45], 0, v[2:3]
	s_movk_i32 s44, 0xaff
	v_lshlrev_b32_e32 v26, 1, v26
	s_movk_i32 s45, 0x3e3
	s_movk_i32 s46, 0x2000
	s_movk_i32 s47, 0x4000
	s_mov_b32 s48, 0x1f1800
	s_movk_i32 s49, 0x7e3
	s_movk_i32 s56, 0x5000
	s_mov_b32 s57, 0xb000
	s_movk_i32 s60, 0x5800
	v_mov_b32_e32 v65, 0x3e3
	v_mov_b32_e32 v66, 0x5800
	v_mov_b32_e32 v67, 0xfffff500
	v_mov_b32_e32 v68, 0x80
	v_mov_b32_e32 v69, 0x63
	s_mov_b32 s61, s13
	v_readlane_b32 s62, v244, 2
	v_readlane_b32 s63, v244, 3
	v_readlane_b32 s66, v244, 6
	v_readlane_b32 s67, v244, 7
	s_branch .Ld1a_268

.Ld1a_268:
	s_cmpk_lt_i32 s61, 0x840
	s_mov_b64 s[0:1], -1
	s_cbranch_scc1 .Ld1a_314
	s_cmpk_gt_i32 s61, 0xaff
	s_mov_b64 s[0:1], -1
	s_cbranch_scc0 .Ld1a_267
	s_lshl_b32 s0, s21, 2
	s_and_b32 s10, s0, 0xf80
	s_cmpk_gt_u32 s61, 0x107f
	s_mov_b64 s[0:1], -1
	s_cbranch_scc0 .Ld1a_267
	s_cmpk_gt_u32 s61, 0x167f
	s_cbranch_scc0 .Ld1a_280
	s_cmpk_gt_u32 s61, 0x187f
	s_cbranch_scc0 .Ld1a_275
	s_lshr_b32 s8, s21, 5
	s_lshr_b32 s4, s20, 7
	s_lshl_b64 s[0:1], s[4:5], 20
	s_and_b32 s4, s8, 15
	s_lshl_b32 s4, s4, 7
	s_or_b32 s0, s0, s4
	s_and_b32 s4, s23, 0x1c0
	v_or_b32_e32 v2, s4, v58
	v_lshl_or_b32 v42, v2, 11, s0
	v_mov_b32_e32 v43, s1
	v_or_b32_e32 v2, s4, v59
	v_lshl_add_u64 v[28:29], v[12:13], 0, v[42:43]
	v_lshl_or_b32 v42, v2, 11, s0
	v_or_b32_e32 v2, s4, v60
	v_lshl_add_u64 v[30:31], v[12:13], 0, v[42:43]
	v_lshl_or_b32 v42, v2, 11, s0
	v_or_b32_e32 v2, s4, v61
	v_lshl_add_u64 v[32:33], v[12:13], 0, v[42:43]
	v_lshl_or_b32 v42, v2, 11, s0
	v_or_b32_e32 v2, s4, v62
	v_lshl_add_u64 v[34:35], v[12:13], 0, v[42:43]
	v_lshl_or_b32 v42, v2, 11, s0
	v_or_b32_e32 v2, s4, v63
	v_lshl_add_u64 v[36:37], v[12:13], 0, v[42:43]
	v_lshl_or_b32 v42, v2, 11, s0
	v_or_b32_e32 v2, s4, v64
	v_lshl_add_u64 v[38:39], v[12:13], 0, v[42:43]
	v_lshl_or_b32 v42, v2, 11, s0
	v_or_b32_e32 v2, s4, v1
	v_lshl_add_u64 v[40:41], v[12:13], 0, v[42:43]
	v_lshl_or_b32 v42, v2, 11, s0
	v_lshl_add_u64 v[42:43], v[12:13], 0, v[42:43]
	s_mov_b64 s[0:1], 0
	v_mov_b32_e32 v2, v57

.Ld1a_end:
	s_mov_b64 s[4:5], s[98:99]
.LBB0_183:
	s_cmp_gt_i32 s31, 3
	s_cselect_b64 s[0:1], -1, 0
	s_and_b64 s[4:5], s[4:5], s[0:1]
	s_andn2_b64 vcc, exec, s[4:5]
	s_cbranch_vccnz .LBB0_243
	s_waitcnt vmcnt(0)
	s_waitcnt vmcnt(0)
	s_barrier
	s_and_saveexec_b64 s[4:5], s[16:17]
	s_cbranch_execz .LBB0_242
	s_add_i32 s6, 0, 0x20160
	v_mov_b32_e32 v1, s6
	s_waitcnt vmcnt(0) expcnt(0) lgkmcnt(0)
	ds_read_b32 v3, v1
	s_add_i32 s6, 0, 0x20164
	v_mov_b32_e32 v1, s6
	ds_read_b32 v1, v1
	s_waitcnt lgkmcnt(1)
	v_cmp_ne_u32_e32 vcc, 0, v3
	s_cbranch_vccnz .LBB0_200
	s_load_dwordx2 s[10:11], s[94:95], 0x4
	s_add_u32 s6, s28, 0x1200
	s_addc_u32 s7, s29, 0
	s_add_u32 s8, s28, 0x1400
	s_addc_u32 s9, s29, 0
	s_waitcnt lgkmcnt(0)
	s_mul_i32 s20, s10, s3
	s_add_u32 s10, s28, 0x1500
	s_mul_i32 s20, s20, s11
	s_addc_u32 s11, s29, 0
	s_add_u32 s12, s28, 0x1600
	s_addc_u32 s13, s29, 0
	s_add_u32 s14, s28, 0x1700
	s_addc_u32 s15, s29, 0
	s_add_u32 s18, s28, 0x1800
	s_addc_u32 s19, s29, 0
	s_add_u32 s42, s28, 0x1900
	s_addc_u32 s43, s29, 0
	s_add_u32 s56, s28, 0x1a00
	s_addc_u32 s57, s29, 0
	s_add_u32 s62, s28, 0x1b00
	s_addc_u32 s63, s29, 0
	s_add_u32 s64, s28, 0x1c00
	s_addc_u32 s65, s29, 0
	s_add_u32 s66, s28, 0x1d00
	s_addc_u32 s67, s29, 0
	s_add_u32 s70, s28, 0x1e00
	s_addc_u32 s71, s29, 0
	s_add_u32 s72, s28, 0x1f00
	s_addc_u32 s73, s29, 0
	s_add_u32 s74, s28, 0x2000
	s_addc_u32 s75, s29, 0
	s_add_u32 s76, s28, 0x2100
	s_addc_u32 s77, s29, 0
	s_add_u32 s78, s28, 0x2200
	s_addc_u32 s79, s29, 0
	s_add_u32 s80, s28, 0x2300
	s_addc_u32 s81, s29, 0
	s_mov_b32 s21, 1
	v_mov_b32_e32 v17, 0
	s_branch .LBB0_188

.Ld1b_begin:
	s_mov_b64 s[98:99], s[18:19]
	s_sub_u32 s100, s94, 0xb8
	s_subb_u32 s101, s95, 0
	s_load_dwordx4 s[44:47], s[100:101], 0x60
	s_load_dwordx2 s[48:49], s[100:101], 0x70
	s_load_dwordx2 s[58:59], s[100:101], 0x18
	s_load_dwordx2 s[60:61], s[100:101], 0x20
	s_waitcnt lgkmcnt(0)
	s_cmpk_gt_i32 s3, 0xe0
	s_cselect_b32 s12, 0xe0, 0
	s_cmp_lt_i32 s2, s12
	s_cbranch_scc1 .Ld1b_end
	s_sub_i32 s0, s2, s12
	s_lshl_b32 s13, s0, 3
	s_add_i32 s13, s13, s33
	s_sub_i32 s14, s3, s12
	s_cmpk_gt_u32 s13, 0x197f
	s_cbranch_scc1 .Ld1b_end
	v_lshlrev_b32_e32 v2, 3, v0
	s_lshl_b32 s4, s33, 14
	v_lshrrev_b32_e32 v19, 3, v164
	v_and_b32_e32 v26, 56, v2
	s_add_i32 s0, s4, 0
	v_mul_u32_u24_e32 v2, 0x84, v26
	v_lshlrev_b32_e32 v13, 2, v19
	v_mov_b32_e32 v3, 0
	v_add3_u32 v44, s0, v2, v13
	v_lshlrev_b32_e32 v2, 1, v26
	v_lshl_add_u64 v[10:11], s[28:29], 0, v[2:3]
	s_mov_b64 s[0:1], 0x2900000
	v_lshl_add_u64 v[4:5], v[10:11], 0, s[0:1]
	s_mov_b64 s[0:1], 0x2300000
	s_lshl_b32 s15, s14, 3
	v_lshl_add_u64 v[6:7], v[10:11], 0, s[0:1]
	s_mov_b64 s[0:1], 0x1d80000
	s_add_u32 s18, s28, 0x2e00000
	v_lshl_add_u64 v[8:9], v[10:11], 0, s[0:1]
	s_mov_b64 s[0:1], 0x1280000
	s_addc_u32 s19, s29, 0
	v_lshl_add_u64 v[10:11], v[10:11], 0, s[0:1]
	s_lshl_b32 s0, s2, 3
	v_lshrrev_b32_e32 v1, 5, v164
	v_mov_b32_e32 v2, 0x6000
	s_add_i32 s0, s33, s0
	s_lshl_b32 s1, s12, 3
	v_and_b32_e32 v12, 31, v0
	v_lshl_or_b32 v49, v19, 13, v2
	v_mul_u32_u24_e32 v2, 0x84, v1
	s_sub_i32 s0, s0, s1
	v_and_b32_e32 v48, 16, v13
	v_or_b32_e32 v55, 0x80c, v13
	v_or_b32_e32 v56, 12, v13
	v_or_b32_e32 v13, s4, v2
	v_lshlrev_b32_e32 v2, 2, v12
	s_add_i32 s20, s0, 0xffffe780
	s_lshl_b32 s0, s3, 8
	s_lshl_b32 s1, s12, 8
	v_bfe_u32 v18, v0, 5, 1
	v_add3_u32 v57, v13, v2, 0
	v_lshl_add_u64 v[12:13], s[60:61], 0, v[2:3]
	s_sub_i32 s22, s0, s1
	s_lshl_b32 s0, s3, 5
	s_lshl_b32 s1, s12, 5
	v_readlane_b32 s60, v244, 0
	v_mul_u32_u24_e32 v20, 0x3000, v18
	s_sub_i32 s24, s0, s1
	v_readlane_b32 s61, v244, 1
	v_readlane_b32 s64, v244, 4
	v_readlane_b32 s65, v244, 5
	s_lshl_b32 s0, s13, 1
	s_lshl_b32 s1, s3, 4
	s_lshl_b32 s4, s12, 4
	v_mul_hi_u32_u24_e32 v21, 0x3000, v18
	v_or_b32_e32 v20, v20, v2
	s_mov_b32 s5, 0
	v_or_b32_e32 v45, 8, v19
	v_or_b32_e32 v46, 16, v19
	v_or_b32_e32 v47, 24, v19
	v_or_b32_e32 v50, 0x800, v48
	v_or_b32_e32 v51, 0x804, v48
	v_or_b32_e32 v52, 4, v48
	v_or_b32_e32 v53, 0x808, v48
	v_or_b32_e32 v54, 8, v48
	s_lshl_b32 s21, s13, 5
	v_or_b32_e32 v58, 14, v1
	s_lshl_b32 s23, s13, 2
	v_or_b32_e32 v59, 12, v1
	v_or_b32_e32 v60, 10, v1
	v_or_b32_e32 v61, 8, v1
	v_or_b32_e32 v62, 6, v1
	v_or_b32_e32 v63, 4, v1
	v_or_b32_e32 v64, 2, v1
	v_lshl_add_u64 v[14:15], s[64:65], 0, v[2:3]
	s_add_i32 s25, s0, 0x7fffd300
	s_sub_i32 s26, s1, s4
	v_lshl_add_u64 v[16:17], s[48:49], 0, v[2:3]
	v_lshl_add_u64 v[20:21], s[48:49], 0, v[20:21]
	v_lshl_add_u64 v[22:23], s[46:47], 0, v[2:3]
	s_add_i32 s27, s0, 0x7fffea00
	v_lshl_add_u64 v[24:25], s[44:45], 0, v[2:3]
	s_movk_i32 s44, 0xaff
	v_lshlrev_b32_e32 v26, 1, v26
	s_movk_i32 s45, 0x3e3
	s_movk_i32 s46, 0x2000
	s_movk_i32 s47, 0x4000
	s_mov_b32 s48, 0x1f1800
	s_movk_i32 s49, 0x7e3
	s_movk_i32 s56, 0x5000
	s_mov_b32 s57, 0xb000
	s_movk_i32 s60, 0x5800
	v_mov_b32_e32 v65, 0x3e3
	v_mov_b32_e32 v66, 0x5800
	v_mov_b32_e32 v67, 0xfffff500
	v_mov_b32_e32 v68, 0x80
	v_mov_b32_e32 v69, 0x63
	s_mov_b32 s61, s13
	v_readlane_b32 s62, v244, 2
	v_readlane_b32 s63, v244, 3
	v_readlane_b32 s66, v244, 6
	v_readlane_b32 s67, v244, 7
	s_branch .Ld1b_268

.Ld1b_268:
	s_cmpk_gt_i32 s61, 0xaff
	s_cbranch_scc1 .Ld1b_end
	s_cmpk_lt_i32 s61, 0x840
	s_cbranch_scc1 .Ld1b_267
	s_mov_b64 s[0:1], -1
	s_branch .Ld1b_314
	s_lshl_b32 s0, s21, 2
	s_and_b32 s10, s0, 0xf80
	s_cmpk_gt_u32 s61, 0x107f
	s_mov_b64 s[0:1], -1
	s_cbranch_scc0 .Ld1b_309
	s_cmpk_gt_u32 s61, 0x167f
	s_cbranch_scc0 .Ld1b_280
	s_cmpk_gt_u32 s61, 0x187f
	s_cbranch_scc0 .Ld1b_275
	s_lshr_b32 s8, s21, 5
	s_lshr_b32 s4, s20, 7
	s_lshl_b64 s[0:1], s[4:5], 20
	s_and_b32 s4, s8, 15
	s_lshl_b32 s4, s4, 7
	s_or_b32 s0, s0, s4
	s_and_b32 s4, s23, 0x1c0
	v_or_b32_e32 v2, s4, v58
	v_lshl_or_b32 v42, v2, 11, s0
	v_mov_b32_e32 v43, s1
	v_or_b32_e32 v2, s4, v59
	v_lshl_add_u64 v[28:29], v[12:13], 0, v[42:43]
	v_lshl_or_b32 v42, v2, 11, s0
	v_or_b32_e32 v2, s4, v60
	v_lshl_add_u64 v[30:31], v[12:13], 0, v[42:43]
	v_lshl_or_b32 v42, v2, 11, s0
	v_or_b32_e32 v2, s4, v61
	v_lshl_add_u64 v[32:33], v[12:13], 0, v[42:43]
	v_lshl_or_b32 v42, v2, 11, s0
	v_or_b32_e32 v2, s4, v62
	v_lshl_add_u64 v[34:35], v[12:13], 0, v[42:43]
	v_lshl_or_b32 v42, v2, 11, s0
	v_or_b32_e32 v2, s4, v63
	v_lshl_add_u64 v[36:37], v[12:13], 0, v[42:43]
	v_lshl_or_b32 v42, v2, 11, s0
	v_or_b32_e32 v2, s4, v64
	v_lshl_add_u64 v[38:39], v[12:13], 0, v[42:43]
	v_lshl_or_b32 v42, v2, 11, s0
	v_or_b32_e32 v2, s4, v1
	v_lshl_add_u64 v[40:41], v[12:13], 0, v[42:43]
	v_lshl_or_b32 v42, v2, 11, s0
	v_lshl_add_u64 v[42:43], v[12:13], 0, v[42:43]
	s_mov_b64 s[0:1], 0
	v_mov_b32_e32 v2, v57

.Ld1b_end:
	s_mov_b64 s[18:19], s[98:99]
